# attention items remapped so the 32 WGs of one XCD process all query blocks of the same (batch,head) concurrently (K/V served from that XCD L2), balanced pairing q,31-q
# speedup vs baseline: 1.0394x; 1.0108x over previous
; __device__ __forceinline__ void phase_attn(KP P, int l_, unsigned char* shm) {
;     ...
;     for (int it = blockIdx.x; it < 4096; it += gridDim.x) {
;         const int j = it & 255, pi = 15 - (it >> 8), bh = j >> 1, half = j & 1, b = bh >> 2, h = bh & 3;
;         const int qb = (pi >> 1) * 4 + ((pi & 1) ? (half ? 2 : 3) : (half ? 1 : 0));
;         const int q0 = qb * 64, nt = (qb >> 1) + 1;
;         const size_t tok0 = (size_t)b * SEQ;
;         bf16x8 qf[2];
;         { const u16* qp = pA + (tok0 + q0 + rq * 16 + l15) * 1536 + h * 128 + mp * 64 + g * 8;
;           qf[0] = *(const bf16x8*)qp; qf[1] = *(const bf16x8*)(qp + 32); }
;         f32x4 ot[8];
; #pragma unroll
;         for (int e = 0; e < 8; ++e) ot[e] = (f32x4){0.f, 0.f, 0.f, 0.f};
;         float mrun = -INFINITY, lrun = 0.f;
;         uint4 kreg0, kreg1, kreg2, kreg3, vreg0, vreg1, vreg2, vreg3;
;         const int kc_key = (tid >> 3) & 63, kc_ch = tid & 7, vc_e = tid >> 4, vc_ch = tid & 15;
;         const u16* kgb = pA + (tok0 + kc_key) * 1536 + 512 + h * 128 + kc_ch * 8;
;         const u16* vTb = vTg + ((size_t)bh * 128 + vc_e) * SEQ + vc_ch * 8;
;     ...
;         ATT_GLOAD(0); ATT_LSTORE(0); __syncthreads();
.LBB0_2649:
	s_lshr_b32 s0, s62, 8
	s_and_b32 s1, s62, 7
	s_lshl_b32 s1, s1, 4
	s_or_b32 s1, s1, s0
	s_bfe_u32 s52, s62, 0x50003
	s_and_b32 s56, s0, 30
	s_add_i32 s52, s52, s56
	s_and_b32 s52, s52, 31
	s_sub_i32 s56, 31, s52
	s_bitcmp1_b32 s0, 0
	s_cselect_b32 s52, s56, s52
	s_lshr_b32 s56, s52, 1
	s_xor_b32 s57, s52, s56
	s_and_b32 s57, s57, 1
	s_sub_i32 s56, 15, s56
	s_lshl_b32 s56, s56, 8
	s_lshl_b32 s1, s1, 1
	s_or_b32 s98, s56, s1
	s_or_b32 s98, s98, s57
	s_bfe_u32 s0, s98, 0x70001
	s_lshl_b32 s52, s0, 19
	v_lshl_add_u64 v[174:175], v[166:167], 0, s[52:53]
	s_ashr_i32 s52, s98, 8
	s_sub_i32 s52, 15, s52
	s_lshl_b32 s1, s98, 7
	s_and_b32 s56, s98, 1
	s_lshl_b32 s57, s52, 1
	s_and_b32 s1, s1, 0x300
	s_and_b32 s57, s57, 0x7ffffffc
	s_and_b32 s52, s52, 1
	s_xor_b32 s58, s56, 3
	s_cmp_eq_u32 s52, 0
	s_cselect_b32 s52, s56, s58
	s_or_b32 s58, s52, s57
	s_lshl_b32 s56, s98, 8
	s_lshl_b32 s52, s58, 6
	s_and_b32 s59, s56, 0xf800
	s_add_i32 s52, s52, s59
	v_or_b32_e32 v4, s52, v194
	s_lshl_b32 s52, s98, 6
	v_mov_b64_e32 v[0:1], s[50:51]
	s_and_b32 s63, s52, 0x180
	v_mad_u64_u32 v[0:1], s[56:57], v4, s83, v[0:1]
	s_lshl_b32 s52, s63, 1
	s_waitcnt vmcnt(1)
	v_lshl_add_u64 v[18:19], v[0:1], 0, s[52:53]
	v_or_b32_e32 v0, s59, v169
	v_mul_u32_u24_e32 v0, 0x600, v0
	v_lshlrev_b32_e32 v50, 1, v0
	v_mov_b32_e32 v51, v5
	v_lshl_add_u64 v[0:1], s[50:51], 0, v[50:51]
	v_lshl_add_u64 v[0:1], v[0:1], 0, s[52:53]
	v_mov_b32_e32 v173, v5
	s_lshl_b32 s52, s0, 7
	v_lshl_add_u64 v[6:7], v[0:1], 0, v[172:173]
	v_lshl_add_u64 v[0:1], s[52:53], 0, v[158:159]
	s_mov_b32 s0, 0x30000
	v_lshlrev_b64 v[0:1], 12, v[0:1]
	v_add_co_u32_e32 v14, vcc, s0, v6
	v_lshl_add_u64 v[20:21], v[162:163], 0, v[0:1]
	s_nop 0
	v_addc_co_u32_e32 v15, vcc, 0, v7, vcc
	s_mov_b32 s0, 0x20000
	s_waitcnt vmcnt(0)
	v_add_co_u32_e32 v22, vcc, s0, v20
	global_load_dwordx4 v[0:3], v[6:7], off offset:1024
	s_nop 0
	global_load_dwordx4 v[6:9], v[6:7], off offset:1152
	s_nop 0
	global_load_dwordx4 v[10:13], v[14:15], off offset:1024
	global_load_dwordx4 v[26:29], v[20:21], off
	v_addc_co_u32_e32 v23, vcc, 0, v21, vcc
	global_load_dwordx4 v[14:17], v[14:15], off offset:1152
	s_nop 0
	global_load_dwordx4 v[30:33], v[22:23], off
	v_add_co_u32_e32 v22, vcc, s85, v20
	s_mov_b32 s0, 0x60000
	s_nop 0
	v_addc_co_u32_e32 v23, vcc, 0, v21, vcc
	v_add_co_u32_e32 v20, vcc, s0, v20
	v_lshl_add_u64 v[18:19], v[154:155], 1, v[18:19]
	v_mov_b32_e32 v171, v5
	v_addc_co_u32_e32 v21, vcc, 0, v21, vcc
	global_load_dwordx4 v[34:37], v[22:23], off
	global_load_dwordx4 v[38:41], v[20:21], off
	v_lshl_add_u64 v[22:23], v[18:19], 0, v[170:171]
	global_load_dwordx4 v[18:21], v[22:23], off
	s_nop 0
	global_load_dwordx4 v[22:25], v[22:23], off offset:64
	v_mov_b32_e32 v70, v5
	v_mov_b32_e32 v71, v5
	v_mov_b32_e32 v72, v5
	v_mov_b32_e32 v73, v5
	v_mov_b64_e32 v[66:67], v[70:71]
	v_mov_b64_e32 v[62:63], v[70:71]
	v_mov_b64_e32 v[54:55], v[70:71]
	v_mov_b64_e32 v[46:47], v[70:71]
	v_mov_b64_e32 v[42:43], v[70:71]
	s_and_b32 s65, s58, 0x7ffffffe
	v_or3_b32 v176, v168, s1, v50
	v_mov_b64_e32 v[50:51], v[70:71]
	v_mov_b64_e32 v[58:59], v[70:71]
	s_mov_b32 s52, 0
	v_mov_b32_e32 v177, v157
	v_mov_b32_e32 v171, 0
	v_mov_b32_e32 v248, 0
	v_mov_b32_e32 v249, 0
	v_mov_b32_e32 v250, 0
	v_mov_b32_e32 v251, 0
	v_mov_b32_e32 v252, 0xff800000
	v_mov_b32_e32 v253, 0xff800000
	v_mov_b64_e32 v[68:69], v[72:73]
	v_mov_b64_e32 v[64:65], v[72:73]
	v_mov_b64_e32 v[56:57], v[72:73]
	v_mov_b64_e32 v[48:49], v[72:73]
	v_mov_b64_e32 v[44:45], v[72:73]
	s_lshr_b32 s59, s58, 1
	s_add_i32 s64, s58, -1
	s_add_i32 s65, s65, 2
	v_mov_b64_e32 v[52:53], v[72:73]
	v_mov_b64_e32 v[60:61], v[72:73]
	s_mov_b32 s70, 0
	s_waitcnt vmcnt(9)
	ds_write_b128 v190, v[0:3]
	s_waitcnt vmcnt(8)
	ds_write_b128 v190, v[6:9] offset:18432
	s_waitcnt vmcnt(7)
	ds_write_b128 v190, v[10:13] offset:9216
	s_waitcnt vmcnt(5)
	ds_write_b128 v190, v[14:17] offset:27648
	ds_write_b128 v192, v[26:29] offset:36864
	s_waitcnt vmcnt(4)
	ds_write_b128 v192, v[30:33] offset:45568
	s_waitcnt vmcnt(3)
	ds_write_b128 v192, v[34:37] offset:54272
	s_waitcnt vmcnt(2)
	ds_write_b128 v192, v[38:41] offset:62976
	s_waitcnt vmcnt(0) lgkmcnt(0)
	s_barrier
	s_branch .LBB0_2651
